# NSA Slc/Win QK^T: K-fragment ds_reads software-pipelined 4-8 deep with counted lgkmcnt instead of read-wait-mfma per fragment
# speedup vs baseline: 1.0171x; 1.0027x over previous
.LBB0_1916:
	s_add_i32 s21, s20, -8
	v_mov_b32_e32 v18, s21
	ds_read_b32 v18, v18
	v_mov_b32_e32 v112, 0xff800000
	v_mov_b32_e32 v113, 0xff800000
	v_mov_b32_e32 v114, 0xff800000
	v_mov_b32_e32 v115, 0xff800000
	s_waitcnt lgkmcnt(0)
	v_readfirstlane_b32 s2, v18
	s_lshl_b32 s2, s2, 6
	s_cmp_gt_i32 s2, s8
	v_mov_b32_e32 v116, 0xff800000
	v_mov_b32_e32 v117, 0xff800000
	v_mov_b32_e32 v118, 0xff800000
	v_mov_b32_e32 v119, 0xff800000
	v_mov_b32_e32 v120, 0xff800000
	v_mov_b32_e32 v121, 0xff800000
	v_mov_b32_e32 v122, 0xff800000
	v_mov_b32_e32 v123, 0xff800000
	v_mov_b32_e32 v124, 0xff800000
	v_mov_b32_e32 v125, 0xff800000
	v_mov_b32_e32 v126, 0xff800000
	v_mov_b32_e32 v127, 0xff800000
	v_mov_b32_e32 v96, 0xff800000
	v_mov_b32_e32 v97, 0xff800000
	v_mov_b32_e32 v98, 0xff800000
	v_mov_b32_e32 v99, 0xff800000
	v_mov_b32_e32 v100, 0xff800000
	v_mov_b32_e32 v101, 0xff800000
	v_mov_b32_e32 v102, 0xff800000
	v_mov_b32_e32 v103, 0xff800000
	v_mov_b32_e32 v104, 0xff800000
	v_mov_b32_e32 v105, 0xff800000
	v_mov_b32_e32 v106, 0xff800000
	v_mov_b32_e32 v107, 0xff800000
	v_mov_b32_e32 v108, 0xff800000
	v_mov_b32_e32 v109, 0xff800000
	v_mov_b32_e32 v110, 0xff800000
	v_mov_b32_e32 v111, 0xff800000
	s_cbranch_scc1 .LBB0_1921
	v_readfirstlane_b32 s2, v18
	s_lshl_b32 s2, s2, 6
	s_or_b32 s2, s2, 63
	v_mov_b32_e32 v111, 0xff800000
	s_cmp_le_i32 s2, s16
	v_mov_b32_e32 v110, 0xff800000
	v_mov_b32_e32 v109, 0xff800000
	v_mov_b32_e32 v108, 0xff800000
	v_mov_b32_e32 v107, 0xff800000
	v_mov_b32_e32 v106, 0xff800000
	v_mov_b32_e32 v105, 0xff800000
	v_mov_b32_e32 v104, 0xff800000
	v_mov_b32_e32 v103, 0xff800000
	v_mov_b32_e32 v102, 0xff800000
	v_mov_b32_e32 v101, 0xff800000
	v_mov_b32_e32 v100, 0xff800000
	v_mov_b32_e32 v99, 0xff800000
	v_mov_b32_e32 v98, 0xff800000
	v_mov_b32_e32 v97, 0xff800000
	v_mov_b32_e32 v96, 0xff800000
	v_mov_b32_e32 v127, 0xff800000
	v_mov_b32_e32 v126, 0xff800000
	v_mov_b32_e32 v125, 0xff800000
	v_mov_b32_e32 v124, 0xff800000
	v_mov_b32_e32 v123, 0xff800000
	v_mov_b32_e32 v122, 0xff800000
	v_mov_b32_e32 v121, 0xff800000
	v_mov_b32_e32 v120, 0xff800000
	v_mov_b32_e32 v119, 0xff800000
	v_mov_b32_e32 v118, 0xff800000
	v_mov_b32_e32 v117, 0xff800000
	v_mov_b32_e32 v116, 0xff800000
	v_mov_b32_e32 v115, 0xff800000
	v_mov_b32_e32 v114, 0xff800000
	v_mov_b32_e32 v113, 0xff800000
	v_mov_b32_e32 v112, 0xff800000
	s_cbranch_scc1 .LBB0_1921
	v_readfirstlane_b32 s2, v18
	s_ashr_i32 s3, s2, 5
	s_lshl_b32 s3, s3, 2
	s_add_i32 s3, s19, s3
	v_mov_b32_e32 v18, s3
	ds_read_b32 v18, v18
	s_waitcnt lgkmcnt(0)
	v_readfirstlane_b32 s3, v18
	s_lshr_b32 s2, s3, s2
	s_bitcmp0_b32 s2, 0
	s_cbranch_scc1 .LBB0_1920
	v_add_u32_e32 v249, v226, v227
	v_add_u32_e32 v248, v226, v228
	v_add_u32_e32 v26, v226, v229
	v_add_u32_e32 v27, v226, v234
	ds_read_b128 v[130:133], v249 offset:49152
	ds_read_b128 v[134:137], v249 offset:57344
	ds_read_b128 v[138:141], v248 offset:49152
	ds_read_b128 v[186:189], v248 offset:57344
	ds_read_b128 v[200:203], v26 offset:49152
	ds_read_b128 v[230:233], v26 offset:57344
	ds_read_b128 v[238:241], v27 offset:49152
	ds_read_b128 v[18:21], v27 offset:57344
	ds_read_b128 v[242:245], v17
	ds_read_b128 v[22:25], v17 offset:1024
	s_waitcnt lgkmcnt(9)
	v_mfma_f32_32x32x16_bf16 v[96:111], v[130:133], v[180:183], 0
	ds_read_b128 v[130:133], v249 offset:49280
	s_waitcnt lgkmcnt(9)
	v_mfma_f32_32x32x16_bf16 v[112:127], v[134:137], v[180:183], 0
	ds_read_b128 v[134:137], v249 offset:57472
	s_waitcnt lgkmcnt(9)
	v_mfma_f32_32x32x16_bf16 v[96:111], v[138:141], v[176:179], v[96:111]
	ds_read_b128 v[138:141], v248 offset:49280
	s_waitcnt lgkmcnt(9)
	v_mfma_f32_32x32x16_bf16 v[112:127], v[186:189], v[176:179], v[112:127]
	ds_read_b128 v[186:189], v248 offset:57472
	s_waitcnt lgkmcnt(9)
	v_mfma_f32_32x32x16_bf16 v[96:111], v[200:203], v[172:175], v[96:111]
	ds_read_b128 v[200:203], v26 offset:49280
	s_waitcnt lgkmcnt(9)
	v_mfma_f32_32x32x16_bf16 v[112:127], v[230:233], v[172:175], v[112:127]
	ds_read_b128 v[230:233], v26 offset:57472
	s_waitcnt lgkmcnt(9)
	v_mfma_f32_32x32x16_bf16 v[96:111], v[238:241], v[168:171], v[96:111]
	ds_read_b128 v[238:241], v27 offset:49280
	s_waitcnt lgkmcnt(9)
	v_mfma_f32_32x32x16_bf16 v[112:127], v[18:21], v[168:171], v[112:127]
	ds_read_b128 v[18:21], v27 offset:57472
	s_waitcnt lgkmcnt(7)
	v_mfma_f32_32x32x16_bf16 v[96:111], v[130:133], v[164:167], v[96:111]
	s_waitcnt lgkmcnt(6)
	v_mfma_f32_32x32x16_bf16 v[112:127], v[134:137], v[164:167], v[112:127]
	s_waitcnt lgkmcnt(5)
	v_mfma_f32_32x32x16_bf16 v[96:111], v[138:141], v[160:163], v[96:111]
	s_waitcnt lgkmcnt(4)
	v_mfma_f32_32x32x16_bf16 v[112:127], v[186:189], v[160:163], v[112:127]
	s_waitcnt lgkmcnt(3)
	v_mfma_f32_32x32x16_bf16 v[96:111], v[200:203], v[242:245], v[96:111]
	s_waitcnt lgkmcnt(2)
	v_mfma_f32_32x32x16_bf16 v[112:127], v[230:233], v[242:245], v[112:127]
	s_waitcnt lgkmcnt(1)
	v_mfma_f32_32x32x16_bf16 v[96:111], v[238:241], v[22:25], v[96:111]
	s_waitcnt lgkmcnt(0)
	v_mfma_f32_32x32x16_bf16 v[112:127], v[18:21], v[22:25], v[112:127]
	s_branch .LBB0_1921

.LBB0_1937:
	v_cndmask_b32_e64 v14, v14, v184, s[2:3]
	v_sub_f32_e32 v15, v96, v14
	v_sub_f32_e32 v22, v98, v14
	v_sub_f32_e32 v23, v100, v14
	v_sub_f32_e32 v24, v102, v14
	v_sub_f32_e32 v25, v104, v14
	v_sub_f32_e32 v26, v106, v14
	v_sub_f32_e32 v27, v108, v14
	v_sub_f32_e32 v28, v110, v14
	v_exp_f32_e32 v96, v15
	v_exp_f32_e32 v98, v22
	v_exp_f32_e32 v100, v23
	v_exp_f32_e32 v102, v24
	v_exp_f32_e32 v104, v25
	v_exp_f32_e32 v106, v26
	v_exp_f32_e32 v108, v27
	v_exp_f32_e32 v110, v28
	s_waitcnt lgkmcnt(0)
	s_barrier
	v_mov_b32_e32 v15, s22
	ds_read_b32 v15, v15
	v_mov_b32_e32 v128, 0xff800000
	v_mov_b32_e32 v129, 0xff800000
	v_mov_b32_e32 v130, 0xff800000
	v_mov_b32_e32 v131, 0xff800000
	s_waitcnt lgkmcnt(0)
	v_readfirstlane_b32 s2, v15
	s_lshl_b32 s2, s2, 6
	s_cmp_gt_i32 s2, s8
	v_mov_b32_e32 v132, 0xff800000
	v_mov_b32_e32 v133, 0xff800000
	v_mov_b32_e32 v134, 0xff800000
	v_mov_b32_e32 v135, 0xff800000
	v_mov_b32_e32 v136, 0xff800000
	v_mov_b32_e32 v137, 0xff800000
	v_mov_b32_e32 v138, 0xff800000
	v_mov_b32_e32 v139, 0xff800000
	v_mov_b32_e32 v140, 0xff800000
	v_mov_b32_e32 v141, 0xff800000
	v_mov_b32_e32 v142, 0xff800000
	v_mov_b32_e32 v143, 0xff800000
	v_mov_b32_e32 v144, 0xff800000
	v_mov_b32_e32 v145, 0xff800000
	v_mov_b32_e32 v146, 0xff800000
	v_mov_b32_e32 v147, 0xff800000
	v_mov_b32_e32 v148, 0xff800000
	v_mov_b32_e32 v149, 0xff800000
	v_mov_b32_e32 v150, 0xff800000
	v_mov_b32_e32 v151, 0xff800000
	v_mov_b32_e32 v152, 0xff800000
	v_mov_b32_e32 v153, 0xff800000
	v_mov_b32_e32 v154, 0xff800000
	v_mov_b32_e32 v155, 0xff800000
	v_mov_b32_e32 v156, 0xff800000
	v_mov_b32_e32 v157, 0xff800000
	v_mov_b32_e32 v158, 0xff800000
	v_mov_b32_e32 v159, 0xff800000
	s_cbranch_scc1 .LBB0_1942
	v_readfirstlane_b32 s2, v15
	s_lshl_b32 s2, s2, 6
	s_or_b32 s2, s2, 63
	v_mov_b32_e32 v159, 0xff800000
	s_cmp_le_i32 s2, s16
	v_mov_b32_e32 v158, 0xff800000
	v_mov_b32_e32 v157, 0xff800000
	v_mov_b32_e32 v156, 0xff800000
	v_mov_b32_e32 v155, 0xff800000
	v_mov_b32_e32 v154, 0xff800000
	v_mov_b32_e32 v153, 0xff800000
	v_mov_b32_e32 v152, 0xff800000
	v_mov_b32_e32 v151, 0xff800000
	v_mov_b32_e32 v150, 0xff800000
	v_mov_b32_e32 v149, 0xff800000
	v_mov_b32_e32 v148, 0xff800000
	v_mov_b32_e32 v147, 0xff800000
	v_mov_b32_e32 v146, 0xff800000
	v_mov_b32_e32 v145, 0xff800000
	v_mov_b32_e32 v144, 0xff800000
	v_mov_b32_e32 v143, 0xff800000
	v_mov_b32_e32 v142, 0xff800000
	v_mov_b32_e32 v141, 0xff800000
	v_mov_b32_e32 v140, 0xff800000
	v_mov_b32_e32 v139, 0xff800000
	v_mov_b32_e32 v138, 0xff800000
	v_mov_b32_e32 v137, 0xff800000
	v_mov_b32_e32 v136, 0xff800000
	v_mov_b32_e32 v135, 0xff800000
	v_mov_b32_e32 v134, 0xff800000
	v_mov_b32_e32 v133, 0xff800000
	v_mov_b32_e32 v132, 0xff800000
	v_mov_b32_e32 v131, 0xff800000
	v_mov_b32_e32 v130, 0xff800000
	v_mov_b32_e32 v129, 0xff800000
	v_mov_b32_e32 v128, 0xff800000
	s_cbranch_scc1 .LBB0_1942
	v_readfirstlane_b32 s2, v15
	s_ashr_i32 s3, s2, 5
	s_lshl_b32 s3, s3, 2
	s_add_i32 s3, s19, s3
	v_mov_b32_e32 v15, s3
	ds_read_b32 v15, v15
	s_waitcnt lgkmcnt(0)
	v_readfirstlane_b32 s3, v15
	s_lshr_b32 s2, s3, s2
	s_bitcmp0_b32 s2, 0
	s_cbranch_scc1 .LBB0_1941
	v_add_u32_e32 v15, v226, v227
	v_add_u32_e32 v249, v226, v228
	v_add_u32_e32 v184, v226, v229
	v_add_u32_e32 v185, v226, v234
	ds_read_b128 v[186:189], v15 offset:32768
	ds_read_b128 v[200:203], v15 offset:40960
	ds_read_b128 v[230:233], v249 offset:32768
	ds_read_b128 v[22:25], v249 offset:40960
	ds_read_b128 v[242:245], v17
	ds_read_b128 v[26:29], v17 offset:1024
	s_waitcnt lgkmcnt(5)
	v_mfma_f32_32x32x16_bf16 v[144:159], v[186:189], v[180:183], 0
	ds_read_b128 v[186:189], v184 offset:32768
	s_waitcnt lgkmcnt(5)
	v_mfma_f32_32x32x16_bf16 v[128:143], v[200:203], v[180:183], 0
	ds_read_b128 v[200:203], v184 offset:40960
	s_waitcnt lgkmcnt(5)
	v_mfma_f32_32x32x16_bf16 v[144:159], v[230:233], v[176:179], v[144:159]
	ds_read_b128 v[230:233], v185 offset:32768
	s_waitcnt lgkmcnt(5)
	v_mfma_f32_32x32x16_bf16 v[128:143], v[22:25], v[176:179], v[128:143]
	ds_read_b128 v[22:25], v185 offset:40960
	s_waitcnt lgkmcnt(3)
	v_mfma_f32_32x32x16_bf16 v[144:159], v[186:189], v[172:175], v[144:159]
	ds_read_b128 v[186:189], v15 offset:32896
	s_waitcnt lgkmcnt(3)
	v_mfma_f32_32x32x16_bf16 v[128:143], v[200:203], v[172:175], v[128:143]
	ds_read_b128 v[200:203], v15 offset:41088
	s_waitcnt lgkmcnt(3)
	v_mfma_f32_32x32x16_bf16 v[144:159], v[230:233], v[168:171], v[144:159]
	ds_read_b128 v[230:233], v249 offset:32896
	s_waitcnt lgkmcnt(3)
	v_mfma_f32_32x32x16_bf16 v[128:143], v[22:25], v[168:171], v[128:143]
	ds_read_b128 v[22:25], v249 offset:41088
	s_waitcnt lgkmcnt(3)
	v_mfma_f32_32x32x16_bf16 v[144:159], v[186:189], v[164:167], v[144:159]
	ds_read_b128 v[186:189], v184 offset:32896
	s_waitcnt lgkmcnt(3)
	v_mfma_f32_32x32x16_bf16 v[128:143], v[200:203], v[164:167], v[128:143]
	ds_read_b128 v[200:203], v184 offset:41088
	s_waitcnt lgkmcnt(3)
	v_mfma_f32_32x32x16_bf16 v[144:159], v[230:233], v[160:163], v[144:159]
	ds_read_b128 v[230:233], v185 offset:32896
	s_waitcnt lgkmcnt(3)
	v_mfma_f32_32x32x16_bf16 v[128:143], v[22:25], v[160:163], v[128:143]
	ds_read_b128 v[22:25], v185 offset:41088
	s_waitcnt lgkmcnt(3)
	v_mfma_f32_32x32x16_bf16 v[144:159], v[186:189], v[242:245], v[144:159]
	s_waitcnt lgkmcnt(2)
	v_mfma_f32_32x32x16_bf16 v[128:143], v[200:203], v[242:245], v[128:143]
	s_waitcnt lgkmcnt(1)
	v_mfma_f32_32x32x16_bf16 v[144:159], v[230:233], v[26:29], v[144:159]
	s_waitcnt lgkmcnt(0)
	v_mfma_f32_32x32x16_bf16 v[128:143], v[22:25], v[26:29], v[128:143]
	s_branch .LBB0_1942

.LBB0_1996:
	s_lshl_b32 s5, s0, 6
	s_waitcnt lgkmcnt(0)
	s_barrier
	s_cmp_le_i32 s5, s13
	s_cselect_b64 s[0:1], -1, 0
	s_or_b32 s10, s5, 63
	s_add_i32 s15, s14, 0xfffffe00
	s_cmp_gt_i32 s10, s15
	s_cselect_b64 s[20:21], -1, 0
	s_and_b64 s[20:21], s[0:1], s[20:21]
	v_cndmask_b32_e64 v15, 0, 1, s[20:21]
	v_cmp_ne_u32_e64 s[0:1], 1, v15
	s_andn2_b64 vcc, exec, s[20:21]
	s_cbranch_vccnz .LBB0_1998
	v_lshlrev_b32_e32 v17, 4, v194
	v_lshl_add_u32 v15, v194, 8, 0
	v_and_b32_e32 v17, 0x70, v17
	v_xad_u32 v249, v0, v17, v15
	v_or_b32_e32 v248, 32, v0
	v_xad_u32 v248, v248, v17, v15
	v_or_b32_e32 v24, 64, v0
	v_xad_u32 v26, v24, v17, v15
	v_or_b32_e32 v24, 0x60, v0
	v_xad_u32 v15, v24, v17, v15
	ds_read_b128 v[28:31], v249 offset:32768
	ds_read_b128 v[70:73], v249 offset:40960
	ds_read_b128 v[74:77], v248 offset:32768
	ds_read_b128 v[78:81], v248 offset:40960
	ds_read_b128 v[82:85], v26 offset:32768
	ds_read_b128 v[86:89], v26 offset:40960
	ds_read_b128 v[90:93], v15 offset:32768
	ds_read_b128 v[18:21], v15 offset:40960
	ds_read_b128 v[240:243], v221
	ds_read_b128 v[22:25], v221 offset:1024
	s_waitcnt lgkmcnt(9)
	v_mfma_f32_32x32x16_bf16 v[48:63], v[28:31], v[180:183], 0
	ds_read_b128 v[28:31], v249 offset:32896
	s_waitcnt lgkmcnt(9)
	v_mfma_f32_32x32x16_bf16 v[32:47], v[70:73], v[180:183], 0
	ds_read_b128 v[70:73], v249 offset:41088
	s_waitcnt lgkmcnt(9)
	v_mfma_f32_32x32x16_bf16 v[48:63], v[74:77], v[176:179], v[48:63]
	ds_read_b128 v[74:77], v248 offset:32896
	s_waitcnt lgkmcnt(9)
	v_mfma_f32_32x32x16_bf16 v[32:47], v[78:81], v[176:179], v[32:47]
	ds_read_b128 v[78:81], v248 offset:41088
	s_waitcnt lgkmcnt(9)
	v_mfma_f32_32x32x16_bf16 v[48:63], v[82:85], v[172:175], v[48:63]
	ds_read_b128 v[82:85], v26 offset:32896
	s_waitcnt lgkmcnt(9)
	v_mfma_f32_32x32x16_bf16 v[32:47], v[86:89], v[172:175], v[32:47]
	ds_read_b128 v[86:89], v26 offset:41088
	s_waitcnt lgkmcnt(9)
	v_mfma_f32_32x32x16_bf16 v[48:63], v[90:93], v[168:171], v[48:63]
	ds_read_b128 v[90:93], v15 offset:32896
	s_waitcnt lgkmcnt(9)
	v_mfma_f32_32x32x16_bf16 v[32:47], v[18:21], v[168:171], v[32:47]
	ds_read_b128 v[18:21], v15 offset:41088
	s_waitcnt lgkmcnt(7)
	v_mfma_f32_32x32x16_bf16 v[48:63], v[28:31], v[164:167], v[48:63]
	s_waitcnt lgkmcnt(6)
	v_mfma_f32_32x32x16_bf16 v[32:47], v[70:73], v[164:167], v[32:47]
	s_waitcnt lgkmcnt(5)
	v_mfma_f32_32x32x16_bf16 v[48:63], v[74:77], v[160:163], v[48:63]
	s_waitcnt lgkmcnt(4)
	v_mfma_f32_32x32x16_bf16 v[32:47], v[78:81], v[160:163], v[32:47]
	s_waitcnt lgkmcnt(3)
	v_mfma_f32_32x32x16_bf16 v[48:63], v[82:85], v[240:243], v[48:63]
	s_waitcnt lgkmcnt(2)
	v_mfma_f32_32x32x16_bf16 v[32:47], v[86:89], v[240:243], v[32:47]
	s_waitcnt lgkmcnt(1)
	v_mfma_f32_32x32x16_bf16 v[48:63], v[90:93], v[22:25], v[48:63]
	s_waitcnt lgkmcnt(0)
	v_mfma_f32_32x32x16_bf16 v[32:47], v[18:21], v[22:25], v[32:47]
	s_branch .LBB0_1999

.LBB0_2008:
	s_add_i32 s4, s21, 0xffffff81
	s_cmp_le_i32 s4, s13
	s_cselect_b64 s[2:3], -1, 0
	s_sub_i32 s5, s21, 64
	s_cmp_gt_i32 s5, s15
	s_cselect_b64 s[10:11], -1, 0
	s_and_b64 s[10:11], s[2:3], s[10:11]
	v_cndmask_b32_e64 v17, 0, 1, s[10:11]
	v_cmp_ne_u32_e64 s[2:3], 1, v17
	s_andn2_b64 vcc, exec, s[10:11]
	s_cbranch_vccnz .LBB0_2010
	ds_read_b128 v[26:29], v234 offset:49152
	ds_read_b128 v[130:133], v234 offset:57344
	ds_read_b128 v[134:137], v235 offset:49152
	ds_read_b128 v[138:141], v235 offset:57344
	ds_read_b128 v[184:187], v236 offset:49152
	ds_read_b128 v[200:203], v236 offset:57344
	ds_read_b128 v[230:233], v237 offset:49152
	ds_read_b128 v[18:21], v237 offset:57344
	ds_read_b128 v[242:245], v221
	ds_read_b128 v[22:25], v221 offset:1024
	s_waitcnt lgkmcnt(9)
	v_mfma_f32_32x32x16_bf16 v[96:111], v[26:29], v[180:183], 0
	ds_read_b128 v[26:29], v234 offset:49280
	s_waitcnt lgkmcnt(9)
	v_mfma_f32_32x32x16_bf16 v[112:127], v[130:133], v[180:183], 0
	ds_read_b128 v[130:133], v234 offset:57472
	s_waitcnt lgkmcnt(9)
	v_mfma_f32_32x32x16_bf16 v[96:111], v[134:137], v[176:179], v[96:111]
	ds_read_b128 v[134:137], v235 offset:49280
	s_waitcnt lgkmcnt(9)
	v_mfma_f32_32x32x16_bf16 v[112:127], v[138:141], v[176:179], v[112:127]
	ds_read_b128 v[138:141], v235 offset:57472
	s_waitcnt lgkmcnt(9)
	v_mfma_f32_32x32x16_bf16 v[96:111], v[184:187], v[172:175], v[96:111]
	ds_read_b128 v[184:187], v236 offset:49280
	s_waitcnt lgkmcnt(9)
	v_mfma_f32_32x32x16_bf16 v[112:127], v[200:203], v[172:175], v[112:127]
	ds_read_b128 v[200:203], v236 offset:57472
	s_waitcnt lgkmcnt(9)
	v_mfma_f32_32x32x16_bf16 v[96:111], v[230:233], v[168:171], v[96:111]
	ds_read_b128 v[230:233], v237 offset:49280
	s_waitcnt lgkmcnt(9)
	v_mfma_f32_32x32x16_bf16 v[112:127], v[18:21], v[168:171], v[112:127]
	ds_read_b128 v[18:21], v237 offset:57472
	s_waitcnt lgkmcnt(7)
	v_mfma_f32_32x32x16_bf16 v[96:111], v[26:29], v[164:167], v[96:111]
	s_waitcnt lgkmcnt(6)
	v_mfma_f32_32x32x16_bf16 v[112:127], v[130:133], v[164:167], v[112:127]
	s_waitcnt lgkmcnt(5)
	v_mfma_f32_32x32x16_bf16 v[96:111], v[134:137], v[160:163], v[96:111]
	s_waitcnt lgkmcnt(4)
	v_mfma_f32_32x32x16_bf16 v[112:127], v[138:141], v[160:163], v[112:127]
	s_waitcnt lgkmcnt(3)
	v_mfma_f32_32x32x16_bf16 v[96:111], v[184:187], v[242:245], v[96:111]
	s_waitcnt lgkmcnt(2)
	v_mfma_f32_32x32x16_bf16 v[112:127], v[200:203], v[242:245], v[112:127]
	s_waitcnt lgkmcnt(1)
	v_mfma_f32_32x32x16_bf16 v[96:111], v[230:233], v[22:25], v[96:111]
	s_waitcnt lgkmcnt(0)
	v_mfma_f32_32x32x16_bf16 v[112:127], v[18:21], v[22:25], v[112:127]
	s_branch .LBB0_2011

.LBB0_2020:
	v_cndmask_b32_e64 v14, v14, v188, s[4:5]
	v_sub_f32_e32 v15, v96, v14
	v_sub_f32_e32 v17, v98, v14
	v_sub_f32_e32 v18, v100, v14
	v_sub_f32_e32 v19, v102, v14
	v_sub_f32_e32 v20, v104, v14
	v_sub_f32_e32 v21, v106, v14
	v_sub_f32_e32 v22, v108, v14
	v_sub_f32_e32 v23, v110, v14
	v_exp_f32_e32 v96, v15
	v_exp_f32_e32 v98, v17
	v_exp_f32_e32 v100, v18
	v_exp_f32_e32 v102, v19
	v_exp_f32_e32 v104, v20
	v_exp_f32_e32 v106, v21
	v_exp_f32_e32 v108, v22
	v_exp_f32_e32 v110, v23
	s_waitcnt lgkmcnt(0)
	s_barrier
	s_cmp_le_i32 s34, s13
	s_cselect_b64 s[4:5], -1, 0
	s_cmp_gt_i32 s21, s15
	s_cselect_b64 s[10:11], -1, 0
	s_and_b64 s[10:11], s[4:5], s[10:11]
	v_cndmask_b32_e64 v15, 0, 1, s[10:11]
	v_cmp_ne_u32_e64 s[4:5], 1, v15
	s_andn2_b64 vcc, exec, s[10:11]
	s_cbranch_vccnz .LBB0_2022
	ds_read_b128 v[18:21], v234 offset:32768
	ds_read_b128 v[26:29], v234 offset:40960
	ds_read_b128 v[188:191], v235 offset:32768
	ds_read_b128 v[200:203], v235 offset:40960
	ds_read_b128 v[230:233], v236 offset:32768
	ds_read_b128 v[242:245], v221
	ds_read_b128 v[22:25], v221 offset:1024
	s_waitcnt lgkmcnt(6)
	v_mfma_f32_32x32x16_bf16 v[144:159], v[18:21], v[180:183], 0
	ds_read_b128 v[18:21], v236 offset:40960
	s_waitcnt lgkmcnt(6)
	v_mfma_f32_32x32x16_bf16 v[128:143], v[26:29], v[180:183], 0
	ds_read_b128 v[26:29], v237 offset:32768
	s_waitcnt lgkmcnt(6)
	v_mfma_f32_32x32x16_bf16 v[144:159], v[188:191], v[176:179], v[144:159]
	ds_read_b128 v[188:191], v237 offset:40960
	s_waitcnt lgkmcnt(6)
	v_mfma_f32_32x32x16_bf16 v[128:143], v[200:203], v[176:179], v[128:143]
	ds_read_b128 v[200:203], v234 offset:32896
	s_waitcnt lgkmcnt(6)
	v_mfma_f32_32x32x16_bf16 v[144:159], v[230:233], v[172:175], v[144:159]
	ds_read_b128 v[230:233], v234 offset:41088
	s_waitcnt lgkmcnt(4)
	v_mfma_f32_32x32x16_bf16 v[128:143], v[18:21], v[172:175], v[128:143]
	ds_read_b128 v[18:21], v235 offset:32896
	s_waitcnt lgkmcnt(4)
	v_mfma_f32_32x32x16_bf16 v[144:159], v[26:29], v[168:171], v[144:159]
	ds_read_b128 v[26:29], v235 offset:41088
	s_waitcnt lgkmcnt(4)
	v_mfma_f32_32x32x16_bf16 v[128:143], v[188:191], v[168:171], v[128:143]
	ds_read_b128 v[188:191], v236 offset:32896
	s_waitcnt lgkmcnt(4)
	v_mfma_f32_32x32x16_bf16 v[144:159], v[200:203], v[164:167], v[144:159]
	ds_read_b128 v[200:203], v236 offset:41088
	s_waitcnt lgkmcnt(4)
	v_mfma_f32_32x32x16_bf16 v[128:143], v[230:233], v[164:167], v[128:143]
	ds_read_b128 v[230:233], v237 offset:32896
	s_waitcnt lgkmcnt(4)
	v_mfma_f32_32x32x16_bf16 v[144:159], v[18:21], v[160:163], v[144:159]
	ds_read_b128 v[18:21], v237 offset:41088
	s_waitcnt lgkmcnt(4)
	v_mfma_f32_32x32x16_bf16 v[128:143], v[26:29], v[160:163], v[128:143]
	s_waitcnt lgkmcnt(3)
	v_mfma_f32_32x32x16_bf16 v[144:159], v[188:191], v[242:245], v[144:159]
	s_waitcnt lgkmcnt(2)
	v_mfma_f32_32x32x16_bf16 v[128:143], v[200:203], v[242:245], v[128:143]
	s_waitcnt lgkmcnt(1)
	v_mfma_f32_32x32x16_bf16 v[144:159], v[230:233], v[22:25], v[144:159]
	s_waitcnt lgkmcnt(0)
	v_mfma_f32_32x32x16_bf16 v[128:143], v[18:21], v[22:25], v[128:143]
	s_branch .LBB0_2023
